# P8: non-temporal F stores only for row-tile group 4 (j >= 16)
# baseline (speedup 1.0000x reference)
.LBB0_898:
	s_mul_i32 s98, s26, 0xccd
	s_lshr_b32 s98, s98, 16
	s_mul_i32 s98, s98, 20
	s_sub_i32 s98, s26, s98
	s_cmp_ge_u32 s98, 16
	s_cselect_b32 s99, 1, 0
	v_max_f32_e32 v125, v125, v125
	v_max_f32_e32 v124, v124, v124
	v_max_f32_e32 v127, v127, v127
	v_max_f32_e32 v126, v126, v126
	v_max_f32_e32 v121, v121, v121
	v_max_f32_e32 v120, v120, v120
	v_max_f32_e32 v123, v123, v123
	v_max_f32_e32 v122, v122, v122
	v_max_f32_e32 v125, 0, v125
	v_max_f32_e32 v124, 0, v124
	v_max_f32_e32 v127, 0, v127
	v_max_f32_e32 v126, 0, v126
	v_max_f32_e32 v121, 0, v121
	v_max_f32_e32 v120, 0, v120
	v_max_f32_e32 v123, 0, v123
	v_max_f32_e32 v122, 0, v122
	v_pk_mul_f32 v[126:127], v[126:127], v[126:127]
	v_pk_mul_f32 v[124:125], v[124:125], v[124:125]
	v_pk_mul_f32 v[152:153], v[122:123], v[122:123]
	v_pk_mul_f32 v[122:123], v[120:121], v[120:121]
	s_nop 7
	v_cvt_pk_bf16_f32 v120, v124, v125
	v_cvt_pk_bf16_f32 v121, v126, v127
	v_cvt_pk_bf16_f32 v122, v122, v123
	v_cvt_pk_bf16_f32 v123, v152, v153
	v_max_f32_e32 v117, 0, v117
	v_max_f32_e32 v116, 0, v116
	v_max_f32_e32 v119, 0, v119
	v_max_f32_e32 v118, 0, v118
	v_max_f32_e32 v113, 0, v113
	v_max_f32_e32 v112, 0, v112
	v_max_f32_e32 v115, 0, v115
	v_max_f32_e32 v114, 0, v114
	ds_write_b128 v147, v[120:123]
	v_pk_mul_f32 v[118:119], v[118:119], v[118:119]
	v_pk_mul_f32 v[116:117], v[116:117], v[116:117]
	v_pk_mul_f32 v[120:121], v[114:115], v[114:115]
	v_pk_mul_f32 v[114:115], v[112:113], v[112:113]
	v_lshl_add_u32 v150, s26, 8, v143
	v_cvt_pk_bf16_f32 v112, v116, v117
	v_cvt_pk_bf16_f32 v113, v118, v119
	v_cvt_pk_bf16_f32 v114, v114, v115
	v_cvt_pk_bf16_f32 v115, v120, v121
	v_ashrrev_i32_e32 v151, 31, v150
	ds_write_b128 v147, v[112:115] offset:64
	v_lshlrev_b64 v[150:151], 13, v[150:151]
	s_lshl_b32 s28, s61, 8
	ds_read_b128 v[114:117], v148
	ds_read_b128 v[118:121], v148 offset:1152
	v_lshl_add_u64 v[150:151], s[4:5], 0, v[150:151]
	s_ashr_i32 s29, s28, 31
	v_lshl_add_u64 v[112:113], s[28:29], 1, v[150:151]
	v_lshl_add_u64 v[112:113], v[112:113], 0, s[8:9]
	v_lshl_add_u64 v[112:113], v[112:113], 0, v[132:133]
	s_waitcnt lgkmcnt(0)
	s_cmp_lg_u32 s99, 0
	s_cbranch_scc1 .Lf8nt_0
	global_store_dwordx4 v[112:113], v[114:117], off
	s_branch .Lf8d_0
